# final-LayerNorm output stores also non-temporal (on top of proj output stores non-temporal)
# baseline (speedup 1.0000x reference)
; __device__ __forceinline__ void final_ln(const bf16_t* ZB, const float* gam, const float* bet, float* yout, int gw, int NGW, int lane) {
;     ...
;     for (int row = gw; row < MR; row += NGW) {
;         const u32x2* zr = (const u32x2*)(ZB + (size_t)row * DM) + lane;
;         f32x4 v[4]; float s = 0.f;
; #pragma unroll
;         for (int j = 0; j < 4; ++j) { const u32x2 raw = zr[64 * j]; v[j] = (f32x4){bflo(raw.x), bfhi(raw.x), bflo(raw.y), bfhi(raw.y)}; s += (v[j].x + v[j].y) + (v[j].z + v[j].w); }
;         const float mean = wave_sum(s) * (1.f / DM); float s2 = 0.f;
; #pragma unroll
;         for (int j = 0; j < 4; ++j) { v[j] = v[j] - mean; s2 += (v[j].x * v[j].x + v[j].y * v[j].y) + (v[j].z * v[j].z + v[j].w * v[j].w); }
;         const float rstd = __builtin_amdgcn_rsqf(wave_sum(s2) * (1.f / DM) + LN_EPS);
;         f32x4* o = (f32x4*)(yout + (size_t)row * DM) + lane;
; #pragma unroll
;         for (int j = 0; j < 4; ++j) o[64 * j] = v[j] * rstd * gv[j] + bv[j];
;     }
.LBB0_2458:
	global_load_dwordx2 v[80:81], v[32:33], off nt
	global_load_dwordx2 v[82:83], v[32:33], off offset:512 nt
	global_load_dwordx2 v[84:85], v[32:33], off offset:1024 nt
	global_load_dwordx2 v[86:87], v[32:33], off offset:1536 nt
	s_add_i32 s8, s8, s10
	v_lshl_add_u64 v[32:33], v[32:33], 0, s[2:3]
	s_cmpk_lt_i32 s8, 0x4080
	v_lshlrev_b32_e32 v53, 16, v45
	v_lshlrev_b32_e32 v52, 16, v44
	v_and_b32_e32 v45, 0xffff0000, v45
	v_and_b32_e32 v44, 0xffff0000, v44
	v_lshlrev_b32_e32 v55, 16, v47
	v_lshlrev_b32_e32 v54, 16, v46
	v_and_b32_e32 v47, 0xffff0000, v47
	v_and_b32_e32 v46, 0xffff0000, v46
	v_pk_add_f32 v[64:65], v[52:53], v[44:45]
	v_pk_add_f32 v[66:67], v[54:55], v[46:47]
	v_lshlrev_b32_e32 v56, 16, v48
	v_and_b32_e32 v57, 0xffff0000, v48
	v_lshlrev_b32_e32 v48, 16, v49
	v_and_b32_e32 v49, 0xffff0000, v49
	v_and_b32_e32 v61, 0xffff0000, v50
	v_add_f32_e32 v43, v64, v65
	v_pk_add_f32 v[64:65], v[66:67], v[66:67] op_sel:[0,1] op_sel_hi:[1,0]
	v_lshlrev_b32_e32 v59, 16, v50
	v_lshlrev_b32_e32 v63, 16, v51
	v_and_b32_e32 v51, 0xffff0000, v51
	v_add_f32_e32 v62, v56, v57
	v_add_f32_e32 v50, v48, v49
	v_add_f32_e32 v58, 0, v43
	v_mov_b32_e32 v65, v61
	v_pk_add_f32 v[66:67], v[62:63], v[50:51]
	v_pk_add_f32 v[64:65], v[58:59], v[64:65]
	s_nop 0
	v_pk_add_f32 v[64:65], v[64:65], v[66:67]
	s_nop 0
	v_add_f32_e32 v43, v64, v65
	ds_bpermute_b32 v50, v36, v43
	s_waitcnt lgkmcnt(0)
	v_add_f32_e32 v43, v43, v50
	ds_bpermute_b32 v50, v37, v43
	s_waitcnt lgkmcnt(0)
	v_add_f32_e32 v43, v43, v50
	ds_bpermute_b32 v50, v38, v43
	s_waitcnt lgkmcnt(0)
	v_add_f32_e32 v43, v43, v50
	ds_bpermute_b32 v50, v39, v43
	s_waitcnt lgkmcnt(0)
	v_add_f32_e32 v43, v43, v50
	ds_bpermute_b32 v50, v40, v43
	s_waitcnt lgkmcnt(0)
	v_add_f32_e32 v43, v43, v50
	ds_bpermute_b32 v50, v41, v43
	s_waitcnt lgkmcnt(0)
	v_add_f32_e32 v43, v43, v50
	v_fmac_f32_e32 v44, 0xba800000, v43
	v_fmac_f32_e32 v45, 0xba800000, v43
	v_fmac_f32_e32 v53, 0xba800000, v43
	v_fmac_f32_e32 v46, 0xba800000, v43
	v_fmac_f32_e32 v47, 0xba800000, v43
	v_fmac_f32_e32 v55, 0xba800000, v43
	v_fmac_f32_e32 v52, 0xba800000, v43
	v_fmac_f32_e32 v54, 0xba800000, v43
	v_fmac_f32_e32 v56, 0xba800000, v43
	v_mov_b32_e32 v64, v53
	v_mov_b32_e32 v65, v45
	v_mov_b32_e32 v53, v44
	v_mov_b32_e32 v44, v55
	v_mov_b32_e32 v45, v47
	v_mov_b32_e32 v55, v46
	v_fmac_f32_e32 v57, 0xba800000, v43
	v_fmac_f32_e32 v48, 0xba800000, v43
	v_mul_f32_e32 v46, v56, v56
	v_pk_mul_f32 v[66:67], v[64:65], v[64:65]
	v_pk_mul_f32 v[68:69], v[52:53], v[52:53]
	v_pk_mul_f32 v[70:71], v[44:45], v[44:45]
	v_pk_mul_f32 v[72:73], v[54:55], v[54:55]
	v_fmac_f32_e32 v49, 0xba800000, v43
	v_fmac_f32_e32 v59, 0xba800000, v43
	v_mul_f32_e32 v58, v48, v48
	v_pk_fma_f32 v[46:47], v[56:57], v[56:57], v[46:47] op_sel_hi:[1,1,0]
	v_pk_mov_b32 v[76:77], v[68:69], v[66:67] op_sel:[1,0]
	v_mov_b32_e32 v69, v67
	v_pk_mov_b32 v[66:67], v[72:73], v[70:71] op_sel:[1,0]
	v_mov_b32_e32 v73, v71
	v_mov_b32_e32 v60, v59
	v_pk_fma_f32 v[74:75], v[48:49], v[48:49], v[58:59] op_sel_hi:[1,1,0]
	v_mul_f32_e32 v46, v59, v59
	v_pk_add_f32 v[58:59], v[76:77], v[68:69]
	v_pk_add_f32 v[66:67], v[66:67], v[72:73]
	v_fmac_f32_e32 v51, 0xba800000, v43
	v_fmac_f32_e32 v63, 0xba800000, v43
	v_fmac_f32_e32 v61, 0xba800000, v43
	v_pk_add_f32 v[58:59], v[58:59], v[58:59] op_sel_hi:[0,1]
	v_pk_add_f32 v[66:67], v[66:67], v[66:67] op_sel_hi:[0,1]
	v_mul_f32_e32 v74, v61, v61
	v_mul_f32_e32 v58, v63, v63
	v_mul_f32_e32 v66, v51, v51
	v_pk_add_f32 v[46:47], v[46:47], v[74:75]
	v_pk_add_f32 v[58:59], v[58:59], v[66:67]
	v_mov_b32_e32 v50, v63
	v_pk_add_f32 v[46:47], v[46:47], v[58:59]
	s_nop 0
	v_add_f32_e32 v43, v46, v47
	ds_bpermute_b32 v46, v36, v43
	s_waitcnt lgkmcnt(0)
	v_add_f32_e32 v43, v43, v46
	ds_bpermute_b32 v46, v37, v43
	s_waitcnt lgkmcnt(0)
	v_add_f32_e32 v43, v43, v46
	ds_bpermute_b32 v46, v38, v43
	s_waitcnt lgkmcnt(0)
	v_add_f32_e32 v43, v43, v46
	ds_bpermute_b32 v46, v39, v43
	s_waitcnt lgkmcnt(0)
	v_add_f32_e32 v43, v43, v46
	ds_bpermute_b32 v46, v40, v43
	s_waitcnt lgkmcnt(0)
	v_add_f32_e32 v43, v43, v46
	ds_bpermute_b32 v46, v41, v43
	s_waitcnt lgkmcnt(0)
	v_add_f32_e32 v43, v43, v46
	v_fmamk_f32 v43, v43, 0x3a800000, v42
	v_rsq_f32_e32 v46, v43
	s_nop 0
	v_pk_mul_f32 v[52:53], v[52:53], v[46:47] op_sel_hi:[1,0]
	v_pk_mul_f32 v[58:59], v[64:65], v[46:47] op_sel_hi:[1,0]
	v_pk_mul_f32 v[54:55], v[54:55], v[46:47] op_sel_hi:[1,0]
	v_pk_mul_f32 v[62:63], v[44:45], v[46:47] op_sel_hi:[1,0]
	v_pk_mul_f32 v[56:57], v[56:57], v[46:47] op_sel_hi:[1,0]
	v_pk_mul_f32 v[64:65], v[48:49], v[46:47] op_sel_hi:[1,0]
	v_pk_mul_f32 v[60:61], v[60:61], v[46:47] op_sel_hi:[1,0]
	v_pk_mul_f32 v[66:67], v[50:51], v[46:47] op_sel_hi:[1,0]
	v_pk_fma_f32 v[46:47], v[2:3], v[58:59], v[6:7]
	v_pk_fma_f32 v[44:45], v[0:1], v[52:53], v[4:5]
	v_pk_fma_f32 v[50:51], v[10:11], v[62:63], v[18:19]
	v_pk_fma_f32 v[48:49], v[8:9], v[54:55], v[16:17]
	v_pk_fma_f32 v[54:55], v[14:15], v[64:65], v[22:23]
	v_pk_fma_f32 v[52:53], v[12:13], v[56:57], v[20:21]
	v_pk_fma_f32 v[58:59], v[26:27], v[66:67], v[30:31]
	v_pk_fma_f32 v[56:57], v[24:25], v[60:61], v[28:29]
	s_waitcnt vmcnt(0)
	global_store_dwordx4 v[34:35], v[44:47], off offset:-3072 sc1 nt
	global_store_dwordx4 v[34:35], v[48:51], off offset:-2048 sc1 nt
	global_store_dwordx4 v[34:35], v[52:55], off offset:-1024 sc1 nt
	global_store_dwordx4 v[34:35], v[56:59], off sc1 nt
	v_lshl_add_u64 v[34:35], v[34:35], 0, s[4:5]
	s_nop 1
	v_mov_b64_e32 v[44:45], v[80:81]
	v_mov_b64_e32 v[46:47], v[82:83]
	v_mov_b64_e32 v[48:49], v[84:85]
	v_mov_b64_e32 v[50:51], v[86:87]
	s_cbranch_scc1 .LBB0_2458
